# weight conversions split three ways: phase 0 keeps first-needed sets; ffn2(l0)+ab_out on the idle SWA half in phase 7; cd_in/cd_out/w_uq/w_ukv on tile-less workgroups in phase 9
# baseline (speedup 1.0000x reference)
; #define LAS __attribute__((address_space(3)))
; __device__ __forceinline__ void conv_matrix(const float* W, int K, int N, const float* gain, bf16_t* WT, int Kd, int mode, int row_off, LAS float* scr, int lane, int gw, int NGW) {
;     const int nblk = N / 32, items = nblk * (K / 64);
;     for (int it = gw; it < items; it += NGW) {
;         const int kb = it / nblk, nb = it % nblk, k0 = 64 * kb, n0 = 32 * nb;
;         float wv[32];
; #pragma unroll
;         for (int i = 0; i < 32; ++i) wv[i] = W[(size_t)(k0 + 2 * i + (lane >> 5)) * N + n0 + (lane & 31)];
; __device__ __forceinline__ void conv_ffn(const LAS Params* PL, int L, int which  , LAS float* scr, int lane, int gw, int NGW) {
;     const float* nrm = PL->in[which ? I_F2N : I_F1N] + (size_t)L * DM;
;     const float* wg = PL->in[which ? I_F2G : I_F1G] + (size_t)L * DM * FF;
;     const float* wu = PL->in[which ? I_F2U : I_F1U] + (size_t)L * DM * FF;
;     const float* wd = PL->in[which ? I_F2D : I_F1D] + (size_t)L * FF * DM;
;     bf16_t* gu = (bf16_t*)(PL->ws + (which ? (L ? WS_WGUC : WS_WGUB) : WS_WGUA)); bf16_t* dn = (bf16_t*)(PL->ws + (which ? (L ? WS_WDC : WS_WDB) : WS_WDA));
;     conv_matrix(wg, DM, FF, nrm, gu, DM, 1, 0, scr, lane, gw, NGW);
.Lconv_entry:
	s_ashr_i32 s5, s22, 6
	s_lshl_b32 s4, s12, 3
	s_add_i32 s4, s5, s4
	s_lshl_b32 s5, s5, 14
	s_lshl_b32 s8, s10, 3
	s_add_i32 s5, s5, 0
	s_cmpk_gt_i32 s4, 0x15ff
	v_and_b32_e32 v1, 63, v54
	s_cbranch_scc1 .LBB0_101
	v_readlane_b32 s9, v254, 2
	s_waitcnt vmcnt(0) lgkmcnt(0)
	v_mov_b32_e32 v19, v0
	v_lshlrev_b32_e32 v11, 3, v1
	v_mov_b32_e32 v2, s9
	v_readlane_b32 s9, v254, 3
	v_lshrrev_b32_e32 v64, 3, v1
	v_lshrrev_b32_e32 v35, 5, v1
	v_mov_b32_e32 v3, s9
	v_readlane_b32 s9, v254, 4
	ds_read_b64 v[8:9], v2
	ds_read2_b64 v[2:5], v3 offset1:1
	v_mov_b32_e32 v6, s9
	v_readlane_b32 s9, v254, 5
	v_mov_b32_e32 v15, v0
	s_mov_b64 s[16:17], 0x1500000
	v_mov_b32_e32 v10, s9
	ds_read_b64 v[6:7], v6
	ds_read_b64 v[12:13], v10
	v_and_b32_e32 v10, 31, v54
	v_lshlrev_b32_e32 v18, 2, v10
	s_lshl_b32 s9, s4, 5
	s_lshl_b32 s22, s4, 6
	s_waitcnt lgkmcnt(0)
	v_lshl_add_u64 v[16:17], v[12:13], 0, v[18:19]
	v_and_b32_e32 v12, 56, v11
	v_mul_u32_u24_e32 v11, 0x84, v12
	v_lshlrev_b32_e32 v14, 1, v12
	v_lshlrev_b32_e32 v13, 2, v64
	v_lshl_add_u64 v[14:15], v[6:7], 0, v[14:15]
	v_add3_u32 v55, s5, v11, v13
	v_mul_u32_u24_e32 v11, 0x84, v35
	v_cmp_ne_u64_e64 s[40:41], 0, v[8:9]
	v_lshl_add_u64 v[14:15], v[14:15], 0, s[16:17]
	v_add3_u32 v56, s5, v18, v11
	v_or_b32_e32 v65, 8, v64
	v_or_b32_e32 v66, 16, v64
	v_or_b32_e32 v67, 24, v64
	s_lshl_b32 s12, s8, 5
	s_lshl_b32 s23, s8, 6
	s_mov_b32 s24, s22
	s_mov_b32 s25, s9
	s_mov_b32 s27, s4
	s_cmp_lg_u32 s58, 0
	s_cbranch_scc1 .Lskip_a1
	s_branch .LBB0_81

; #define LAS __attribute__((address_space(3)))
; __device__ __forceinline__ void conv_matrix(const float* W, int K, int N, const float* gain, bf16_t* WT, int Kd, int mode, int row_off, LAS float* scr, int lane, int gw, int NGW) {
;     const int nblk = N / 32, items = nblk * (K / 64);
;     for (int it = gw; it < items; it += NGW) {
;         const int kb = it / nblk, nb = it % nblk, k0 = 64 * kb, n0 = 32 * nb;
;         float wv[32];
; #pragma unroll
;         for (int i = 0; i < 32; ++i) wv[i] = W[(size_t)(k0 + 2 * i + (lane >> 5)) * N + n0 + (lane & 31)];
; __device__ __forceinline__ void conv_ffn(const LAS Params* PL, int L, int which  , LAS float* scr, int lane, int gw, int NGW) {
;     ...
;     conv_matrix(wu, DM, FF, nrm, gu, DM, 2, 0, scr, lane, gw, NGW);
.LBB0_85:
	v_lshlrev_b32_e32 v10, 2, v10
	v_mov_b32_e32 v11, v0
	v_lshl_add_u64 v[2:3], v[2:3], 0, v[10:11]
	s_mov_b32 s24, s22
	s_mov_b32 s25, s9
	s_mov_b32 s27, s4
	s_cmp_lg_u32 s58, 0
	s_cbranch_scc1 .LBB0_89
	s_branch .LBB0_87

; #define LAS __attribute__((address_space(3)))
; __device__ __forceinline__ void conv_matrix(const float* W, int K, int N, const float* gain, bf16_t* WT, int Kd, int mode, int row_off, LAS float* scr, int lane, int gw, int NGW) {
;     const int nblk = N / 32, items = nblk * (K / 64);
;     for (int it = gw; it < items; it += NGW) {
;         const int kb = it / nblk, nb = it % nblk, k0 = 64 * kb, n0 = 32 * nb;
;         float wv[32];
; #pragma unroll
;         for (int i = 0; i < 32; ++i) wv[i] = W[(size_t)(k0 + 2 * i + (lane >> 5)) * N + n0 + (lane & 31)];
; __device__ __forceinline__ void conv_ffn(const LAS Params* PL, int L, int which  , LAS float* scr, int lane, int gw, int NGW) {
;     ...
;     conv_matrix(wd, FF, DM, nullptr, dn, FF, 0, 0, scr, lane, gw, NGW);
.LBB0_89:
	v_mov_b32_e32 v11, v0
	v_lshlrev_b32_e32 v12, 1, v12
	v_mov_b32_e32 v13, v0
	v_lshl_add_u64 v[2:3], v[4:5], 0, v[10:11]
	v_lshl_add_u64 v[4:5], v[6:7], 0, v[12:13]
	s_mov_b64 s[16:17], 0x4100000
	v_lshl_add_u64 v[4:5], v[4:5], 0, s[16:17]
	s_mul_i32 s16, s4, 0x2c000
	v_mov_b32_e32 v6, s16
	s_movk_i32 s16, 0x1600
	v_mad_u32_u24 v68, v64, s16, v6
	s_mul_i32 s24, s8, 0x2c000
	s_mov_b32 s25, s9
	v_mov_b32_e32 v6, v68
	s_mov_b32 s27, s4
	s_cmp_lg_u32 s58, 0
	s_cbranch_scc1 .Lskip_a3

; #define LAS __attribute__((address_space(3)))
; __device__ __forceinline__ void conv_matrix(const float* W, int K, int N, const float* gain, bf16_t* WT, int Kd, int mode, int row_off, LAS float* scr, int lane, int gw, int NGW) {
;     const int nblk = N / 32, items = nblk * (K / 64);
;     for (int it = gw; it < items; it += NGW) {
;         const int kb = it / nblk, nb = it % nblk, k0 = 64 * kb, n0 = 32 * nb;
;         float wv[32];
; #pragma unroll
;         for (int i = 0; i < 32; ++i) wv[i] = W[(size_t)(k0 + 2 * i + (lane >> 5)) * N + n0 + (lane & 31)];
; __device__ __forceinline__ void conv_ffn(const LAS Params* PL, int L, int which  , LAS float* scr, int lane, int gw, int NGW) {
;     const float* nrm = PL->in[which ? I_F2N : I_F1N] + (size_t)L * DM;
;     const float* wg = PL->in[which ? I_F2G : I_F1G] + (size_t)L * DM * FF;
;     const float* wu = PL->in[which ? I_F2U : I_F1U] + (size_t)L * DM * FF;
;     const float* wd = PL->in[which ? I_F2D : I_F1D] + (size_t)L * FF * DM;
;     bf16_t* gu = (bf16_t*)(PL->ws + (which ? (L ? WS_WGUC : WS_WGUB) : WS_WGUA)); bf16_t* dn = (bf16_t*)(PL->ws + (which ? (L ? WS_WDC : WS_WDB) : WS_WDA));
;     conv_matrix(wg, DM, FF, nrm, gu, DM, 1, 0, scr, lane, gw, NGW);
.Lskip_a3:
	v_readlane_b32 s16, v254, 6
	v_mov_b32_e32 v13, v0
	s_mov_b32 s25, s22
	v_mov_b32_e32 v2, s16
	v_readlane_b32 s16, v254, 7
	s_mov_b32 s27, s9
	s_mov_b32 s33, s4
	v_mov_b32_e32 v3, s16
	v_readlane_b32 s16, v254, 4
	ds_read_b128 v[6:9], v2
	ds_read_b128 v[2:5], v3
	v_mov_b32_e32 v11, s16
	ds_read_b64 v[14:15], v11
	v_mov_b32_e32 v11, v0
	s_waitcnt lgkmcnt(0)
	v_lshl_add_u64 v[16:17], v[8:9], 0, v[10:11]
	s_mov_b64 s[16:17], 0x5700000
	v_cmp_ne_u64_e64 s[40:41], 0, v[6:7]
	v_lshl_add_u64 v[8:9], v[14:15], 0, v[12:13]
	v_lshl_add_u64 v[8:9], v[8:9], 0, s[16:17]
	s_cmp_lg_u32 s58, 7
	s_cbranch_scc1 .LBB0_95
	s_branch .LBB0_93

; #define LAS __attribute__((address_space(3)))
; __device__ __forceinline__ void conv_matrix(const float* W, int K, int N, const float* gain, bf16_t* WT, int Kd, int mode, int row_off, LAS float* scr, int lane, int gw, int NGW) {
;     const int nblk = N / 32, items = nblk * (K / 64);
;     for (int it = gw; it < items; it += NGW) {
;         const int kb = it / nblk, nb = it % nblk, k0 = 64 * kb, n0 = 32 * nb;
;         float wv[32];
; #pragma unroll
;         for (int i = 0; i < 32; ++i) wv[i] = W[(size_t)(k0 + 2 * i + (lane >> 5)) * N + n0 + (lane & 31)];
; __device__ __forceinline__ void conv_ffn(const LAS Params* PL, int L, int which  , LAS float* scr, int lane, int gw, int NGW) {
;     ...
;     conv_matrix(wu, DM, FF, nrm, gu, DM, 2, 0, scr, lane, gw, NGW);
.LBB0_95:
	v_mov_b32_e32 v11, v0
	v_lshl_add_u64 v[2:3], v[2:3], 0, v[10:11]
	s_mov_b32 s25, s9
	s_mov_b32 s27, s4
	s_cmp_lg_u32 s58, 7
	s_cbranch_scc1 .LBB0_99
	s_branch .LBB0_97

; #define LAS __attribute__((address_space(3)))
; __device__ __forceinline__ void conv_matrix(const float* W, int K, int N, const float* gain, bf16_t* WT, int Kd, int mode, int row_off, LAS float* scr, int lane, int gw, int NGW) {
;     const int nblk = N / 32, items = nblk * (K / 64);
;     for (int it = gw; it < items; it += NGW) {
;         const int kb = it / nblk, nb = it % nblk, k0 = 64 * kb, n0 = 32 * nb;
;         float wv[32];
; #pragma unroll
;         for (int i = 0; i < 32; ++i) wv[i] = W[(size_t)(k0 + 2 * i + (lane >> 5)) * N + n0 + (lane & 31)];
; __device__ __forceinline__ void conv_ffn(const LAS Params* PL, int L, int which  , LAS float* scr, int lane, int gw, int NGW) {
;     ...
;     conv_matrix(wd, FF, DM, nullptr, dn, FF, 0, 0, scr, lane, gw, NGW);
.LBB0_99:
	v_mov_b32_e32 v11, v0
	v_mov_b32_e32 v13, v0
	v_lshl_add_u64 v[2:3], v[4:5], 0, v[10:11]
	v_lshl_add_u64 v[4:5], v[14:15], 0, v[12:13]
	s_mov_b64 s[16:17], 0x8300000
	v_lshl_add_u64 v[4:5], v[4:5], 0, s[16:17]
	s_mov_b32 s22, s4
	s_cmp_lg_u32 s58, 7
	s_cbranch_scc1 .Lskip_b3

; #define LAS __attribute__((address_space(3)))
; __device__ __forceinline__ void conv_matrix(const float* W, int K, int N, const float* gain, bf16_t* WT, int Kd, int mode, int row_off, LAS float* scr, int lane, int gw, int NGW) {
;     const int nblk = N / 32, items = nblk * (K / 64);
;     for (int it = gw; it < items; it += NGW) {
;         const int kb = it / nblk, nb = it % nblk, k0 = 64 * kb, n0 = 32 * nb;
;         float wv[32];
; #pragma unroll
;         for (int i = 0; i < 32; ++i) wv[i] = W[(size_t)(k0 + 2 * i + (lane >> 5)) * N + n0 + (lane & 31)];
; __global__ void __launch_bounds__(NTHREADS, 2) hybrid_fwd(Params P) {
;     ...
;             conv_matrix(PL->in[I_ABIN], DM, ABN, PL->in[I_MIXN], (bf16_t*)(ws + WS_WABIN), DM, 0, 0, scr, lane, gw, NGW);
.Lskip_b3:
.LBB0_101:
	s_cmp_lg_u32 s58, 0
	s_cbranch_scc1 .LBB0_106
	s_cmpk_gt_i32 s4, 0x131f
	s_cbranch_scc1 .LBB0_106
	v_readlane_b32 s9, v254, 8
	v_lshlrev_b32_e32 v6, 2, v54
	v_and_b32_e32 v6, 0x7c, v6
	s_waitcnt lgkmcnt(0)
	v_mov_b32_e32 v2, s9
	v_readlane_b32 s9, v254, 9
	v_mov_b32_e32 v7, v0
	v_add_u32_e32 v8, s5, v6
	v_mov_b32_e32 v4, s9
	ds_read_b64 v[2:3], v2
	ds_read_b64 v[4:5], v4
	v_lshrrev_b32_e32 v44, 3, v1
	v_lshrrev_b32_e32 v35, 5, v1
	v_lshlrev_b32_e32 v10, 2, v44
	s_mov_b64 s[16:17], 0x9900000
	s_waitcnt lgkmcnt(0)
	v_lshl_add_u64 v[4:5], v[4:5], 0, v[6:7]
	v_lshlrev_b32_e32 v6, 3, v1
	v_and_b32_e32 v6, 56, v6
	v_mul_u32_u24_e32 v9, 0x84, v6
	v_lshlrev_b32_e32 v6, 1, v6
	v_lshl_add_u64 v[6:7], s[0:1], 0, v[6:7]
	v_add3_u32 v45, s5, v9, v10
	v_mul_u32_u24_e32 v9, 0x84, v35
	v_cmp_ne_u64_e64 s[38:39], 0, v[2:3]
	v_lshl_add_u64 v[6:7], v[6:7], 0, s[16:17]
	s_lshl_b32 s9, s4, 5
	s_lshl_b32 s12, s8, 5
	v_add_u32_e32 v46, v8, v9
	s_mov_b32 s22, s4
	s_branch .LBB0_104

; #define LAS __attribute__((address_space(3)))
; __device__ __forceinline__ void conv_matrix(const float* W, int K, int N, const float* gain, bf16_t* WT, int Kd, int mode, int row_off, LAS float* scr, int lane, int gw, int NGW) {
;     const int nblk = N / 32, items = nblk * (K / 64);
;     for (int it = gw; it < items; it += NGW) {
;         const int kb = it / nblk, nb = it % nblk, k0 = 64 * kb, n0 = 32 * nb;
;         float wv[32];
; #pragma unroll
;         for (int i = 0; i < 32; ++i) wv[i] = W[(size_t)(k0 + 2 * i + (lane >> 5)) * N + n0 + (lane & 31)];
; __global__ void __launch_bounds__(NTHREADS, 2) hybrid_fwd(Params P) {
;     ...
;             conv_matrix(PL->in[I_ABOUT], DM, DM, nullptr, (bf16_t*)(ws + WS_WABOUT), DM, 0, 0, scr, lane, gw, NGW);
.LBB0_106:
	s_cmpk_lt_i32 s4, 0x800
	s_cselect_b64 s[16:17], -1, 0
	s_cmpk_gt_i32 s4, 0x7ff
	s_cbranch_scc1 .LBB0_109
	v_readlane_b32 s9, v254, 10
	v_lshlrev_b32_e32 v4, 2, v54
	s_waitcnt lgkmcnt(0)
	v_mov_b32_e32 v5, v0
	v_mov_b32_e32 v2, s9
	ds_read_b64 v[2:3], v2
	v_and_b32_e32 v4, 0x7c, v4
	v_add_u32_e32 v9, s5, v4
	v_lshrrev_b32_e32 v7, 3, v1
	v_lshrrev_b32_e32 v6, 5, v1
	s_waitcnt lgkmcnt(0)
	v_lshl_add_u64 v[2:3], v[2:3], 0, v[4:5]
	v_lshlrev_b32_e32 v4, 3, v1
	v_and_b32_e32 v4, 56, v4
	v_mul_u32_u24_e32 v8, 0x84, v4
	v_lshlrev_b32_e32 v4, 1, v4
	v_lshlrev_b32_e32 v10, 2, v7
	v_lshl_add_u64 v[4:5], s[0:1], 0, v[4:5]
	s_mov_b64 s[18:19], 0xad00000
	v_add3_u32 v8, s5, v8, v10
	v_mul_u32_u24_e32 v10, 0x84, v6
	v_lshl_add_u64 v[4:5], v[4:5], 0, s[18:19]
	s_lshl_b32 s9, s4, 5
	s_lshl_b32 s12, s8, 5
	v_add_u32_e32 v9, v9, v10
	s_mov_b32 s22, s4
	s_cmp_lg_u32 s58, 7
	s_cbranch_scc1 .Lskip_c1

; #define LAS __attribute__((address_space(3)))
; __device__ __forceinline__ void conv_matrix(const float* W, int K, int N, const float* gain, bf16_t* WT, int Kd, int mode, int row_off, LAS float* scr, int lane, int gw, int NGW) {
;     const int nblk = N / 32, items = nblk * (K / 64);
;     for (int it = gw; it < items; it += NGW) {
;         const int kb = it / nblk, nb = it % nblk, k0 = 64 * kb, n0 = 32 * nb;
;         float wv[32];
; #pragma unroll
;         for (int i = 0; i < 32; ++i) wv[i] = W[(size_t)(k0 + 2 * i + (lane >> 5)) * N + n0 + (lane & 31)];
; __global__ void __launch_bounds__(NTHREADS, 2) hybrid_fwd(Params P) {
;     ...
;             conv_matrix(PL->in[I_CDIN], DM, CDN, PL->in[I_MIXN] + DM, (bf16_t*)(ws + WS_WCDIN), DM, 0, 0, scr, lane, gw, NGW);
.Lskip_c1:
.LBB0_109:
	s_cmp_eq_u32 s58, 7
	s_cbranch_scc1 .Lconv_return7
	s_cmpk_gt_i32 s4, 0xf1f
	s_cbranch_scc1 .LBB0_112
	v_readlane_b32 s9, v254, 8
	v_lshlrev_b32_e32 v6, 2, v54
	v_and_b32_e32 v6, 0x7c, v6
	s_waitcnt lgkmcnt(0)
	v_mov_b32_e32 v2, s9
	v_readlane_b32 s9, v254, 11
	ds_read_b64 v[2:3], v2
	v_mov_b32_e32 v7, v0
	v_mov_b32_e32 v4, s9
	ds_read_b64 v[4:5], v4
	v_add_u32_e32 v8, s5, v6
	s_waitcnt vmcnt(0)
	v_lshrrev_b32_e32 v17, 3, v1
	v_lshrrev_b32_e32 v16, 5, v1
	s_mov_b64 s[18:19], 0x2000
	s_waitcnt lgkmcnt(0)
	v_lshl_add_u64 v[4:5], v[4:5], 0, v[6:7]
	v_lshlrev_b32_e32 v6, 3, v1
	v_and_b32_e32 v6, 56, v6
	v_mul_u32_u24_e32 v9, 0x84, v6
	v_lshlrev_b32_e32 v6, 1, v6
	v_lshlrev_b32_e32 v10, 2, v17
	v_lshl_add_u64 v[2:3], v[2:3], 0, s[18:19]
	v_lshl_add_u64 v[6:7], s[0:1], 0, v[6:7]
	s_mov_b64 s[18:19], 0xb500000
	v_add3_u32 v18, s5, v9, v10
	v_mul_u32_u24_e32 v9, 0x84, v16
	v_lshl_add_u64 v[6:7], v[6:7], 0, s[18:19]
	s_lshl_b32 s9, s4, 5
	s_lshl_b32 s12, s8, 5
	v_add_u32_e32 v19, v8, v9
	s_mov_b32 s18, s4
	s_cmp_lg_u32 s58, 9
	s_cbranch_scc1 .Lskip_c2

; #define LAS __attribute__((address_space(3)))
; __device__ __forceinline__ void conv_matrix(const float* W, int K, int N, const float* gain, bf16_t* WT, int Kd, int mode, int row_off, LAS float* scr, int lane, int gw, int NGW) {
;     const int nblk = N / 32, items = nblk * (K / 64);
;     for (int it = gw; it < items; it += NGW) {
;         const int kb = it / nblk, nb = it % nblk, k0 = 64 * kb, n0 = 32 * nb;
;         float wv[32];
; #pragma unroll
;         for (int i = 0; i < 32; ++i) wv[i] = W[(size_t)(k0 + 2 * i + (lane >> 5)) * N + n0 + (lane & 31)];
; __global__ void __launch_bounds__(NTHREADS, 2) hybrid_fwd(Params P) {
;     ...
;             conv_matrix(PL->in[I_CDOUT], DM, DM, nullptr, (bf16_t*)(ws + WS_WCDOUT), DM, 0, 0, scr, lane, gw, NGW);
.Lskip_c2:
.LBB0_112:
	s_waitcnt lgkmcnt(0)
	v_cndmask_b32_e64 v2, 0, 1, s[16:17]
	v_cmp_ne_u32_e64 s[38:39], 1, v2
	s_andn2_b64 vcc, exec, s[16:17]
	s_cbranch_vccnz .LBB0_115
	v_readlane_b32 s9, v254, 12
	v_lshlrev_b32_e32 v4, 2, v54
	v_mov_b32_e32 v5, v0
	v_mov_b32_e32 v2, s9
	ds_read_b64 v[2:3], v2
	v_and_b32_e32 v4, 0x7c, v4
	v_add_u32_e32 v9, s5, v4
	v_lshrrev_b32_e32 v7, 3, v1
	v_lshrrev_b32_e32 v6, 5, v1
	s_waitcnt lgkmcnt(0)
	v_lshl_add_u64 v[2:3], v[2:3], 0, v[4:5]
	v_lshlrev_b32_e32 v4, 3, v1
	v_and_b32_e32 v4, 56, v4
	v_mul_u32_u24_e32 v8, 0x84, v4
	v_lshlrev_b32_e32 v4, 1, v4
	v_lshlrev_b32_e32 v10, 2, v7
	v_lshl_add_u64 v[4:5], s[0:1], 0, v[4:5]
	s_mov_b64 s[16:17], 0xc500000
	v_add3_u32 v8, s5, v8, v10
	v_mul_u32_u24_e32 v10, 0x84, v6
	v_lshl_add_u64 v[4:5], v[4:5], 0, s[16:17]
	s_lshl_b32 s9, s4, 5
	s_lshl_b32 s12, s8, 5
	v_add_u32_e32 v9, v9, v10
	s_mov_b32 s22, s4
	s_cmp_lg_u32 s58, 9
	s_cbranch_scc1 .Lskip_c3

; #define LAS __attribute__((address_space(3)))
; __device__ __forceinline__ void conv_matrix(const float* W, int K, int N, const float* gain, bf16_t* WT, int Kd, int mode, int row_off, LAS float* scr, int lane, int gw, int NGW) {
;     const int nblk = N / 32, items = nblk * (K / 64);
;     for (int it = gw; it < items; it += NGW) {
;         const int kb = it / nblk, nb = it % nblk, k0 = 64 * kb, n0 = 32 * nb;
;         float wv[32];
; #pragma unroll
;         for (int i = 0; i < 32; ++i) wv[i] = W[(size_t)(k0 + 2 * i + (lane >> 5)) * N + n0 + (lane & 31)];
; __global__ void __launch_bounds__(NTHREADS, 2) hybrid_fwd(Params P) {
;     ...
;             conv_matrix(PL->in[I_WUQ], 512, 1536, PL->in[I_CQN], (bf16_t*)(ws + WS_WUQ), 512, 0, 0, scr, lane, gw, NGW);
.Lskip_c3:
.LBB0_115:
	s_cmpk_gt_i32 s4, 0x17f
	s_cbranch_scc1 .LBB0_120
	v_readlane_b32 s9, v254, 13
	v_lshlrev_b32_e32 v6, 2, v54
	v_and_b32_e32 v6, 0x7c, v6
	v_mov_b32_e32 v2, s9
	v_readlane_b32 s9, v254, 14
	v_mov_b32_e32 v7, v0
	v_add_u32_e32 v8, s5, v6
	v_mov_b32_e32 v4, s9
	ds_read_b64 v[2:3], v2
	ds_read_b64 v[4:5], v4
	v_lshrrev_b32_e32 v44, 3, v1
	v_lshrrev_b32_e32 v35, 5, v1
	v_lshlrev_b32_e32 v10, 2, v44
	s_mov_b64 s[16:17], 0xcd00000
	s_waitcnt lgkmcnt(0)
	v_lshl_add_u64 v[4:5], v[4:5], 0, v[6:7]
	v_lshlrev_b32_e32 v6, 3, v1
	v_and_b32_e32 v6, 56, v6
	v_mul_u32_u24_e32 v9, 0x84, v6
	v_lshlrev_b32_e32 v6, 1, v6
	v_lshl_add_u64 v[6:7], s[0:1], 0, v[6:7]
	v_add3_u32 v45, s5, v9, v10
	v_mul_u32_u24_e32 v9, 0x84, v35
	v_cmp_ne_u64_e64 s[40:41], 0, v[2:3]
	v_lshl_add_u64 v[6:7], v[6:7], 0, s[16:17]
	s_lshl_b32 s9, s4, 5
	s_lshl_b32 s12, s8, 5
	v_add_u32_e32 v46, v8, v9
	s_mov_b32 s22, s4
	s_cmp_lg_u32 s58, 9
	s_cbranch_scc1 .LBB0_120
	s_branch .LBB0_118

; #define LAS __attribute__((address_space(3)))
; __device__ __forceinline__ void conv_matrix(const float* W, int K, int N, const float* gain, bf16_t* WT, int Kd, int mode, int row_off, LAS float* scr, int lane, int gw, int NGW) {
;     const int nblk = N / 32, items = nblk * (K / 64);
;     for (int it = gw; it < items; it += NGW) {
;         const int kb = it / nblk, nb = it % nblk, k0 = 64 * kb, n0 = 32 * nb;
;         float wv[32];
; #pragma unroll
;         for (int i = 0; i < 32; ++i) wv[i] = W[(size_t)(k0 + 2 * i + (lane >> 5)) * N + n0 + (lane & 31)];
; __global__ void __launch_bounds__(NTHREADS, 2) hybrid_fwd(Params P) {
;     ...
;             conv_matrix(PL->in[I_WUKV], 256, 2048, PL->in[I_CKVN], (bf16_t*)(ws + WS_WUKV), 256, 0, 0, scr, lane, gw, NGW);
.LBB0_122:
	s_andn2_b64 vcc, exec, s[16:17]
	s_cbranch_vccnz .LBB0_127
	v_readlane_b32 s9, v254, 15
	v_mov_b32_e32 v11, v0
	v_lshrrev_b32_e32 v35, 5, v1
	v_mov_b32_e32 v2, s9
	v_readlane_b32 s9, v254, 16
	v_lshrrev_b32_e32 v52, 3, v1
	s_mov_b64 s[16:17], 0xcf00000
	v_mov_b32_e32 v3, s9
	ds_read_b64 v[6:7], v2
	ds_read_b64 v[4:5], v3
	v_and_b32_e32 v2, 31, v54
	v_lshlrev_b32_e32 v10, 2, v2
	v_add_u32_e32 v12, s5, v10
	v_lshlrev_b32_e32 v13, 2, v52
	s_waitcnt lgkmcnt(0)
	v_lshl_add_u64 v[8:9], v[4:5], 0, v[10:11]
	v_lshlrev_b32_e32 v4, 3, v1
	v_and_b32_e32 v4, 56, v4
	v_lshlrev_b32_e32 v10, 1, v4
	v_mul_u32_u24_e32 v48, 0x84, v4
	v_lshl_add_u64 v[10:11], s[0:1], 0, v[10:11]
	v_mul_u32_u24_e32 v49, 0x84, v35
	v_mov_b32_e32 v3, v0
	v_cmp_ne_u64_e64 s[40:41], 0, v[6:7]
	v_mov_b32_e32 v5, v0
	v_lshl_add_u64 v[10:11], v[10:11], 0, s[16:17]
	v_add3_u32 v50, s5, v48, v13
	v_or_b32_e32 v53, 8, v52
	v_or_b32_e32 v55, 16, v52
	v_or_b32_e32 v56, 24, v52
	s_lshl_b32 s9, s4, 5
	s_lshl_b32 s12, s8, 5
	v_add_u32_e32 v51, v12, v49
	s_mov_b32 s18, s4
	s_cmp_lg_u32 s58, 9
	s_cbranch_scc1 .LBB0_127
	s_branch .LBB0_125

; #define LAS __attribute__((address_space(3)))
; __device__ __forceinline__ void conv_matrix(const float* W, int K, int N, const float* gain, bf16_t* WT, int Kd, int mode, int row_off, LAS float* scr, int lane, int gw, int NGW) {
;     const int nblk = N / 32, items = nblk * (K / 64);
;     for (int it = gw; it < items; it += NGW) {
;         const int kb = it / nblk, nb = it % nblk, k0 = 64 * kb, n0 = 32 * nb;
;         float wv[32];
; #pragma unroll
;         for (int i = 0; i < 32; ++i) wv[i] = W[(size_t)(k0 + 2 * i + (lane >> 5)) * N + n0 + (lane & 31)];
; __global__ void __launch_bounds__(NTHREADS, 2) hybrid_fwd(Params P) {
;     ...
;             for (int l2 = 0; l2 < 2; ++l2) {
;                 conv_matrix(PL->in[I_MXWQ] + (size_t)l2 * DM * 512, DM, 512, PL->in[I_MXN] + l2 * DM, (bf16_t*)(ws + WS_WMQ) + (size_t)l2 * 512 * DM, DM, 0, 0, scr, lane, gw, NGW);
;                 conv_matrix(PL->in[I_MXWO] + (size_t)l2 * 512 * DM, 512, DM, nullptr, (bf16_t*)(ws + WS_WMO) + (size_t)l2 * DM * 512, 512, 0, 0, scr, lane, gw, NGW);
.LBB0_127:
	s_cmp_eq_u32 s58, 9
	s_cbranch_scc1 .Lconv_return9
	v_lshl_add_u64 v[4:5], v[4:5], 1, s[0:1]
	s_mov_b64 s[18:19], 0xd000000
	s_cmpk_lt_i32 s4, 0x200
	v_lshlrev_b32_e32 v8, 2, v2
	v_add_u32_e32 v9, s5, v48
	v_lshl_add_u64 v[6:7], v[4:5], 0, s[18:19]
	s_mov_b64 s[18:19], 0xd400000
	s_cselect_b64 s[16:17], -1, 0
	v_lshl_add_u32 v57, v52, 2, v9
	v_add3_u32 v58, s5, v8, v49
	v_lshl_add_u32 v59, v53, 2, v9
	v_lshl_add_u32 v60, v55, 2, v9
	v_lshl_add_u32 v61, v56, 2, v9
	v_lshl_add_u64 v[8:9], v[4:5], 0, s[18:19]
	s_mov_b32 s5, 0
	s_mov_b64 s[18:19], -1
	s_branch .LBB0_129

; __global__ void __launch_bounds__(NTHREADS, 2) hybrid_fwd(Params P) {
;     ...
;             pg8::StaticOrder S; S.init(g.M, g.N, G, bx);
;             pg8::gemm_phase<pg8::EpiAny, pg8::StaticOrder, true, true>(lds, g, S, E, tid);
;         }
;         if (EN(6) && ph == 5) { ROOTS
.LBB0_428:
	s_cmp_eq_u32 s58, 9
	s_cbranch_scc0 .Lno_idle_conv
	s_lshr_b32 s10, s56, 1
	s_cmp_ge_u32 s73, s10
	s_cbranch_scc0 .Lno_idle_conv
	v_mov_b32_e32 v54, v236
	s_sub_i32 s12, s73, s10
	s_sub_i32 s10, s56, s10
	s_mov_b64 s[0:1], s[30:31]
	s_movk_i32 s3, 0x5800
	s_movk_i32 s89, 0x3c80
	s_movk_i32 s91, 0x1800
	v_readfirstlane_b32 s22, v54
	s_branch .Lconv_entry
.Lconv_return9:
.Lno_idle_conv:
	s_mov_b32 s92, 0x6dc9c883
	s_mov_b64 s[18:19], -1
	s_mov_b64 s[50:51], 0
	s_cmp_lt_i32 s58, 18
	s_mov_b64 s[0:1], 0
	s_mov_b64 s[4:5], 0
	s_mov_b64 s[8:9], 0
	s_movk_i32 s29, 0x3ff
	s_mov_b32 s93, 0x3fc45f30
	s_cbranch_scc1 .LBB0_435
	s_mov_b64 s[4:5], -1
	s_mov_b64 s[18:19], 0
	s_cmp_gt_i32 s58, 18
	s_cbranch_scc0 .LBB0_435
	s_cmp_gt_i32 s58, 21
	s_cbranch_scc0 .LBB0_432
	s_cmp_eq_u32 s58, 22
	s_mov_b64 s[4:5], 0
	s_cselect_b64 s[8:9], -1, 0

; #define LAS __attribute__((address_space(3)))
; __global__ void __launch_bounds__(NTHREADS, 2) hybrid_fwd(Params P) {
;     ...
;                 const int gw2 = (bx - nscan) * 8 + wave, NGW2 = (G - nscan) * 8;
;                 conv_ffn(PL, 1, 0, (LAS float*)(lds + wave * 16384), lane, gw2, NGW2);
;                 conv_ffn(PL, 1, 1, (LAS float*)(lds + wave * 16384), lane, gw2, NGW2);
.LBB0_734:
	s_lshr_b32 s10, s56, 1
	v_mov_b32_e32 v54, v236
	s_sub_i32 s12, s73, s10
	s_sub_i32 s10, s56, s10
	s_mov_b64 s[0:1], s[30:31]
	s_movk_i32 s3, 0x5800
	s_movk_i32 s89, 0x3c80
	s_movk_i32 s91, 0x1800
	v_readfirstlane_b32 s22, v54
	s_branch .Lconv_entry
